# m3_sample gate loads merged; sample_gemm_resid K=1024: 16 operand loads issued up front
# baseline (speedup 1.0000x reference)
.LBB0_36:
	s_and_b32 s9, s7, 62
	s_or_b32 s10, s9, s4
	s_ashr_i32 s9, s8, 1
	s_and_b32 s9, s9, -16
	s_addk_i32 s9, 0x4000
	v_or_b32_e32 v0, s9, v147
	v_ashrrev_i32_e32 v1, 31, v0
	v_lshlrev_b64 v[0:1], 11, v[0:1]
	v_lshl_or_b32 v23, s10, 4, v147
	v_lshl_add_u64 v[32:33], v[16:17], 0, v[0:1]
	v_lshlrev_b32_e32 v144, 11, v23
	v_lshl_add_u64 v[34:35], v[18:19], 0, v[144:145]
	global_load_dwordx4 v[0:3], v[32:33], off
	global_load_dwordx4 v[4:7], v[34:35], off
	global_load_dwordx4 v[8:11], v[32:33], off offset:64
	global_load_dwordx4 v[12:15], v[34:35], off offset:64
	global_load_dwordx4 v[24:27], v[32:33], off offset:128
	global_load_dwordx4 v[28:31], v[34:35], off offset:128
	global_load_dwordx4 v[212:215], v[32:33], off offset:192
	global_load_dwordx4 v[216:219], v[34:35], off offset:192
	global_load_dwordx4 v[220:223], v[32:33], off offset:256
	global_load_dwordx4 v[224:227], v[34:35], off offset:256
	global_load_dwordx4 v[228:231], v[32:33], off offset:320
	global_load_dwordx4 v[232:235], v[34:35], off offset:320
	global_load_dwordx4 v[236:239], v[32:33], off offset:384
	global_load_dwordx4 v[162:165], v[34:35], off offset:384
	global_load_dwordx4 v[166:169], v[32:33], off offset:448
	global_load_dwordx4 v[172:175], v[34:35], off offset:448
	s_andn2_b64 vcc, exec, s[0:1]
	s_waitcnt vmcnt(14)
	v_mfma_f32_16x16x32_bf16 v[0:3], v[0:3], v[4:7], 0
	s_waitcnt vmcnt(12)
	v_mfma_f32_16x16x32_bf16 v[4:7], v[8:11], v[12:15], 0
	s_waitcnt vmcnt(10)
	v_mfma_f32_16x16x32_bf16 v[0:3], v[24:27], v[28:31], v[0:3]
	s_waitcnt vmcnt(8)
	v_mfma_f32_16x16x32_bf16 v[4:7], v[212:215], v[216:219], v[4:7]
	s_waitcnt vmcnt(6)
	v_mfma_f32_16x16x32_bf16 v[0:3], v[220:223], v[224:227], v[0:3]
	s_waitcnt vmcnt(4)
	v_mfma_f32_16x16x32_bf16 v[4:7], v[228:231], v[232:235], v[4:7]
	s_barrier
	s_waitcnt vmcnt(2)
	v_mfma_f32_16x16x32_bf16 v[0:3], v[236:239], v[162:165], v[0:3]
	s_waitcnt vmcnt(0)
	v_mfma_f32_16x16x32_bf16 v[4:7], v[166:169], v[172:175], v[4:7]
	s_nop 7
	v_pk_add_f32 v[2:3], v[2:3], v[6:7]
	v_pk_add_f32 v[0:1], v[0:1], v[4:5]
	ds_write_b128 v20, v[0:3]
	s_waitcnt lgkmcnt(0)
	s_barrier
	s_cbranch_vccnz .LBB0_35
	v_or_b32_e32 v24, s9, v22
	v_ashrrev_i32_e32 v25, 31, v24
	v_lshlrev_b64 v[26:27], 12, v[24:25]
	v_lshlrev_b32_e32 v23, 2, v23
	v_readlane_b32 s10, v250, 4
	v_or_b32_e32 v26, v26, v23
	v_readlane_b32 s11, v250, 5
	ds_read_b128 v[12:15], v21
	ds_read_b128 v[4:7], v21 offset:2048
	ds_read_b128 v[0:3], v21 offset:4096
	ds_read_b128 v[8:11], v21 offset:6144
	v_lshl_add_u64 v[28:29], s[10:11], 0, v[26:27]
	v_lshl_add_u64 v[26:27], s[66:67], 0, v[26:27]
	global_load_dword v25, v[26:27], off
	v_or_b32_e32 v242, 1, v24
	v_ashrrev_i32_e32 v243, 31, v242
	v_lshlrev_b64 v[242:243], 12, v[242:243]
	v_or_b32_e32 v242, v242, v23
	v_lshl_add_u64 v[242:243], s[66:67], 0, v[242:243]
	global_load_dword v246, v[242:243], off
	v_or_b32_e32 v242, 2, v24
	v_ashrrev_i32_e32 v243, 31, v242
	v_lshlrev_b64 v[242:243], 12, v[242:243]
	v_or_b32_e32 v242, v242, v23
	v_lshl_add_u64 v[242:243], s[66:67], 0, v[242:243]
	global_load_dword v247, v[242:243], off
	v_or_b32_e32 v242, 3, v24
	v_ashrrev_i32_e32 v243, 31, v242
	v_lshlrev_b64 v[242:243], 12, v[242:243]
	v_or_b32_e32 v242, v242, v23
	v_lshl_add_u64 v[242:243], s[66:67], 0, v[242:243]
	global_load_dword v248, v[242:243], off
	s_waitcnt lgkmcnt(3)
	v_mov_b32_e32 v26, v12
	s_waitcnt lgkmcnt(1)
	v_mov_b32_e32 v27, v0
	v_mov_b32_e32 v30, v4
	s_waitcnt lgkmcnt(0)
	v_mov_b32_e32 v31, v8
	v_pk_add_f32 v[26:27], v[26:27], v[30:31]
	v_mov_b32_e32 v8, v5
	v_add_f32_e32 v0, v26, v27
	v_or_b32_e32 v26, 1, v24
	v_ashrrev_i32_e32 v27, 31, v26
	v_lshlrev_b64 v[26:27], 12, v[26:27]
	v_or_b32_e32 v26, v26, v23
	s_nop 0
	s_waitcnt vmcnt(3)
	v_fmac_f32_e32 v0, 0x3fd744fd, v25
	global_store_dword v[28:29], v0, off sc1
	v_lshl_add_u64 v[28:29], s[10:11], 0, v[26:27]
	v_lshl_add_u64 v[26:27], s[66:67], 0, v[26:27]
	s_nop 0
	v_mov_b32_e32 v0, v13
	v_pk_add_f32 v[0:1], v[0:1], v[8:9]
	v_mov_b32_e32 v8, v6
	v_add_f32_e32 v0, v0, v1
	v_mov_b32_e32 v9, v10
	v_mov_b32_e32 v10, v7
	s_nop 0
	s_waitcnt vmcnt(3)
	v_fmac_f32_e32 v0, 0x3fd744fd, v246
	global_store_dword v[28:29], v0, off sc1
	v_or_b32_e32 v0, 2, v24
	v_ashrrev_i32_e32 v1, 31, v0
	v_lshlrev_b64 v[0:1], 12, v[0:1]
	v_or_b32_e32 v0, v0, v23
	v_lshl_add_u64 v[4:5], s[10:11], 0, v[0:1]
	v_lshl_add_u64 v[0:1], s[66:67], 0, v[0:1]
	s_nop 0
	v_mov_b32_e32 v0, v14
	v_mov_b32_e32 v1, v2
	v_pk_add_f32 v[0:1], v[0:1], v[8:9]
	v_mov_b32_e32 v2, v15
	v_add_f32_e32 v0, v0, v1
	s_nop 0
	s_waitcnt vmcnt(3)
	v_fmac_f32_e32 v0, 0x3fd744fd, v247
	global_store_dword v[4:5], v0, off sc1
	v_or_b32_e32 v0, 3, v24
	v_ashrrev_i32_e32 v1, 31, v0
	v_lshlrev_b64 v[0:1], 12, v[0:1]
	v_or_b32_e32 v0, v0, v23
	v_lshl_add_u64 v[4:5], s[10:11], 0, v[0:1]
	v_lshl_add_u64 v[0:1], s[66:67], 0, v[0:1]
	s_nop 0
	v_pk_add_f32 v[0:1], v[2:3], v[10:11]
	s_nop 0
	v_add_f32_e32 v0, v0, v1
	s_nop 0
	s_waitcnt vmcnt(3)
	v_fmac_f32_e32 v0, 0x3fd744fd, v248
	global_store_dword v[4:5], v0, off sc1
	s_branch .LBB0_35

.LBB0_118:
	s_waitcnt lgkmcnt(0)
	ds_read_b128 v[0:3], v125 offset:512
	ds_read_b128 v[6:9], v125
	ds_read_b128 v[10:13], v125 offset:16
	ds_read_b128 v[164:167], v125 offset:32
	ds_read_b128 v[168:171], v125 offset:48
	ds_read_b128 v[172:175], v125 offset:528
	ds_read_b128 v[176:179], v125 offset:544
	ds_read_b128 v[180:183], v125 offset:560
	ds_read_b128 v[184:187], v125 offset:576
	ds_read_b128 v[188:191], v125 offset:64
	ds_read_b128 v[192:195], v125 offset:592
	ds_read_b128 v[212:215], v125 offset:80
	ds_read_b128 v[216:219], v125 offset:608
	ds_read_b128 v[220:223], v125 offset:96
	ds_read_b128 v[224:227], v125 offset:624
	ds_read_b128 v[228:231], v125 offset:112
	ds_read_b128 v[232:235], v126 offset:1536
	ds_read_b128 v[236:239], v126 offset:1552
	ds_read_b128 v[242:245], v126 offset:1568
	ds_read_b128 v[246:249], v126 offset:1584
	s_waitcnt lgkmcnt(14)
	v_fma_f32 v0, v99, v0, 0
	v_fma_f32 v6, v99, v6, 0
	v_fmac_f32_e32 v0, v98, v1
	v_fmac_f32_e32 v6, v98, v7
	v_fmac_f32_e32 v0, v97, v2
	v_fmac_f32_e32 v6, v97, v8
	v_fmac_f32_e32 v0, v96, v3
	v_fmac_f32_e32 v6, v96, v9
	s_waitcnt vmcnt(62)
	v_fmac_f32_e32 v0, v95, v172
	v_fmac_f32_e32 v6, v95, v10
	s_waitcnt vmcnt(61)
	v_fmac_f32_e32 v0, v94, v173
	v_fmac_f32_e32 v6, v94, v11
	s_waitcnt vmcnt(60)
	v_fmac_f32_e32 v0, v92, v174
	v_fmac_f32_e32 v6, v92, v12
	s_waitcnt vmcnt(59)
	v_fmac_f32_e32 v0, v89, v175
	v_fmac_f32_e32 v6, v89, v13
	s_waitcnt vmcnt(58) lgkmcnt(13)
	v_fmac_f32_e32 v0, v90, v176
	v_fmac_f32_e32 v6, v90, v164
	s_waitcnt vmcnt(49)
	v_fmac_f32_e32 v0, v93, v177
	v_fmac_f32_e32 v6, v93, v165
	s_waitcnt vmcnt(48)
	v_fmac_f32_e32 v0, v91, v178
	v_fmac_f32_e32 v6, v91, v166
	s_waitcnt vmcnt(47)
	v_fmac_f32_e32 v0, v88, v179
	v_fmac_f32_e32 v6, v88, v167
	s_waitcnt vmcnt(46) lgkmcnt(12)
	v_fmac_f32_e32 v0, v87, v180
	v_fmac_f32_e32 v6, v87, v168
	s_waitcnt vmcnt(45)
	v_fmac_f32_e32 v0, v86, v181
	v_fmac_f32_e32 v6, v86, v169
	s_waitcnt vmcnt(44)
	v_fmac_f32_e32 v0, v85, v182
	v_fmac_f32_e32 v6, v85, v170
	s_waitcnt vmcnt(43)
	v_fmac_f32_e32 v0, v84, v183
	v_fmac_f32_e32 v6, v84, v171
	s_waitcnt lgkmcnt(11)
	v_fmac_f32_e32 v0, v83, v184
	s_waitcnt vmcnt(34) lgkmcnt(3)
	v_fma_f32 v14, v138, v232, 0
	v_fmac_f32_e32 v6, v83, v188
	v_fmac_f32_e32 v0, v82, v185
	s_waitcnt vmcnt(26)
	v_fma_f32 v15, v162, v232, 0
	v_fmac_f32_e32 v14, v135, v233
	v_fmac_f32_e32 v6, v82, v189
	v_fmac_f32_e32 v0, v81, v186
	s_waitcnt vmcnt(25)
	v_fmac_f32_e32 v15, v147, v233
	v_fmac_f32_e32 v14, v134, v234
	v_fmac_f32_e32 v6, v81, v190
	v_fmac_f32_e32 v0, v80, v187
	s_waitcnt vmcnt(24)
	v_fmac_f32_e32 v15, v143, v234
	v_fmac_f32_e32 v14, v117, v235
	v_fmac_f32_e32 v6, v80, v191
	v_fmac_f32_e32 v0, v27, v192
	s_waitcnt vmcnt(23)
	v_fmac_f32_e32 v15, v141, v235
	s_waitcnt lgkmcnt(2)
	v_fmac_f32_e32 v14, v114, v236
	v_fmac_f32_e32 v6, v27, v212
	v_fmac_f32_e32 v0, v26, v193
	s_waitcnt vmcnt(22)
	v_fmac_f32_e32 v15, v139, v236
	v_fmac_f32_e32 v14, v112, v237
	v_fmac_f32_e32 v6, v26, v213
	v_fmac_f32_e32 v0, v25, v194
	s_waitcnt vmcnt(21)
	v_fmac_f32_e32 v15, v136, v237
	v_fmac_f32_e32 v14, v109, v238
	v_fmac_f32_e32 v6, v25, v214
	v_fmac_f32_e32 v0, v24, v195
	s_waitcnt vmcnt(20)
	v_fmac_f32_e32 v15, v118, v238
	v_fmac_f32_e32 v14, v106, v239
	v_fmac_f32_e32 v6, v24, v215
	v_fmac_f32_e32 v0, v23, v216
	s_waitcnt vmcnt(19)
	v_fmac_f32_e32 v15, v115, v239
	s_waitcnt vmcnt(18) lgkmcnt(1)
	v_fmac_f32_e32 v14, v113, v242
	v_fmac_f32_e32 v6, v23, v220
	v_fmac_f32_e32 v0, v22, v217
	s_waitcnt vmcnt(10)
	v_fmac_f32_e32 v15, v142, v242
	v_fmac_f32_e32 v14, v110, v243
	v_fmac_f32_e32 v6, v22, v221
	v_fmac_f32_e32 v0, v21, v218
	s_waitcnt vmcnt(9)
	v_fmac_f32_e32 v15, v140, v243
	v_fmac_f32_e32 v14, v108, v244
	v_fmac_f32_e32 v6, v21, v222
	v_fmac_f32_e32 v0, v20, v219
	s_waitcnt vmcnt(8)
	v_fmac_f32_e32 v15, v137, v244
	v_fmac_f32_e32 v14, v105, v245
	v_fmac_f32_e32 v6, v20, v223
	v_fmac_f32_e32 v0, v19, v224
	s_waitcnt vmcnt(7)
	v_fmac_f32_e32 v15, v119, v245
	s_waitcnt lgkmcnt(0)
	v_fmac_f32_e32 v14, v103, v246
	v_fmac_f32_e32 v6, v19, v228
	v_fmac_f32_e32 v0, v18, v225
	s_waitcnt vmcnt(6)
	v_fmac_f32_e32 v15, v116, v246
	v_fmac_f32_e32 v14, v102, v247
	v_fmac_f32_e32 v6, v18, v229
	v_fmac_f32_e32 v0, v17, v226
	s_lshl_b32 s20, s31, 1
	s_waitcnt vmcnt(5)
	v_fmac_f32_e32 v15, v111, v247
	v_fmac_f32_e32 v14, v101, v248
	v_fmac_f32_e32 v6, v17, v230
	v_fmac_f32_e32 v0, v16, v227
	s_add_u32 s20, s24, s20
	s_waitcnt vmcnt(4)
	v_fmac_f32_e32 v15, v107, v248
	v_fmac_f32_e32 v14, v100, v249
	v_fmac_f32_e32 v6, v16, v231
	ds_write_b32 v123, v0 offset:2112
	v_add_u32_e32 v0, 64, v128
	s_addc_u32 s21, s25, 0
	s_waitcnt vmcnt(3)
	v_fmac_f32_e32 v15, v104, v249
	ds_write2st64_b32 v0, v6, v14 offset0:16 offset1:24
	ds_write_b32 v128, v15 offset:8256
	s_waitcnt lgkmcnt(0)
	s_barrier
	global_load_ushort v212, v199, s[20:21]
	global_load_ushort v3, v199, s[20:21] offset:16
	v_readlane_b32 s0, v253, 10
	ds_read_b96 v[0:2], v145 offset:2048
	s_nop 0
	s_nop 0
	s_nop 0
	s_or_b32 s20, s31, s0
	s_ashr_i32 s21, s20, 31
	v_readlane_b32 s0, v250, 46
	s_lshl_b64 s[20:21], s[20:21], 2
	v_readlane_b32 s4, v250, 50
	v_readlane_b32 s5, v250, 51
	s_add_u32 s34, s4, s20
	v_readlane_b32 s6, v250, 52
	s_addc_u32 s35, s5, s21
	v_readlane_b32 s7, v250, 53
	s_add_u32 s20, s6, s20
	s_addc_u32 s21, s7, s21
	global_load_dword v6, v145, s[34:35]
	global_load_dword v8, v145, s[20:21]
	v_readlane_b32 s1, v250, 47
	v_readlane_b32 s2, v250, 48
	v_readlane_b32 s3, v250, 49
	v_readlane_b32 s8, v250, 54
	v_readlane_b32 s9, v250, 55
	v_readlane_b32 s10, v250, 56
	v_readlane_b32 s11, v250, 57
	v_readlane_b32 s12, v250, 58
	v_readlane_b32 s13, v250, 59
	v_readlane_b32 s14, v250, 60
	v_readlane_b32 s15, v250, 61
	s_waitcnt vmcnt(0)
	v_lshlrev_b32_e32 v7, 16, v212
	v_add_f32_e32 v7, v8, v7
	v_mul_f32_e64 v8, |v7|, s88
	v_exp_f32_e32 v8, v8
	s_nop 0
	v_cmp_ngt_f32_e32 vcc, s89, v8
	s_cbranch_vccz .LBB0_120
	v_add_f32_e32 v9, 1.0, v8
	v_cmp_gt_f32_e32 vcc, s86, v9
	s_and_b64 s[20:21], vcc, exec
	s_cselect_b32 s20, 32, 0
	v_ldexp_f32 v9, v9, s20
	v_log_f32_e32 v9, v9
	s_nop 0
	v_mul_f32_e32 v10, 0x3f317217, v9
	v_fma_f32 v10, v9, s90, -v10
	v_fmac_f32_e32 v10, 0x3377d1cf, v9
	v_fmac_f32_e32 v10, 0x3f317217, v9
	v_cmp_lt_f32_e64 s[20:21], |v9|, s91
	s_nop 1
	v_cndmask_b32_e64 v9, v9, v10, s[20:21]
	v_cndmask_b32_e32 v10, 0, v205, vcc
	v_sub_f32_e32 v9, v9, v10
	s_movk_i32 s1, 0x4200
	s_mov_b32 s2, 0x2aaaaaab
	s_cbranch_execz .LBB0_121
	s_branch .LBB0_122
